# ret_chunk: decay/mask of the 32 score values branch-free (one batched gtab read, lane-mask select) instead of 32 divergent branches each with an LDS round trip
# speedup vs baseline: 1.0317x; 1.0155x over previous
; #define MFMA32(a, b, c) __builtin_amdgcn_mfma_f32_32x32x16_bf16((a), (b), (c), 0, 0, 0)
; DI void phase_ret_chunk(PrmC p, int ri, unsigned char* smem, bool skip_ctx_out) {
;     ...
; #pragma unroll
;             for (int i = 0; i < 16; ++i) acc[i] *= rowscale;
;             if (use0) {
; #pragma unroll
;                 for (int i = 0; i < 16; ++i) { const int j = (i & 3) + 8 * (i >> 2) + 4 * hh; const bool keep = dir ? (j >= iil) : (iil >= j); Sx0[i] = keep ? Sx0[i] * (gi0 * gtab[hh * 16 + i]) : 0.f; }
; #pragma unroll
;                 for (int s = 0; s < 2; ++s) {
;                     const bf16x8 pb = pack_step(Sx0, s);
;                     const unsigned char* va = smem + R_VTL + (32 * dvt + r) * RT_PITCH + (16 * s + 4 * hh) * 2;
;                     const uint2 lo = *(const uint2*)va, hi = *(const uint2*)(va + 16);
;                     acc = MFMA32(__builtin_bit_cast(bf16x8, make_uint4(lo.x, lo.y, hi.x, hi.y)), pb, acc);
;                 }
.LBB0_380:
	s_or_b64 exec, exec, s[18:19]
	s_nop 5
	v_pk_mul_f32 v[78:79], v[176:177], v[78:79]
	v_pk_mul_f32 v[76:77], v[174:175], v[76:77]
	v_pk_mul_f32 v[74:75], v[172:173], v[74:75]
	v_pk_mul_f32 v[72:73], v[170:171], v[72:73]
	v_pk_mul_f32 v[70:71], v[168:169], v[70:71]
	v_pk_mul_f32 v[68:69], v[166:167], v[68:69]
	v_pk_mul_f32 v[66:67], v[164:165], v[66:67]
	v_pk_mul_f32 v[64:65], v[154:155], v[64:65]
	s_and_saveexec_b64 s[18:19], s[12:13]
	s_cbranch_execz .LBB0_414
	v_add_u32_e32 v128, v132, v187
	ds_read_b32 v2, v128 offset:34816
	ds_read_b32 v0, v128 offset:34820
	ds_read_b32 v4, v128 offset:34824
	ds_read_b32 v3, v128 offset:34828
	ds_read_b32 v6, v128 offset:34832
	ds_read_b32 v5, v128 offset:34836
	ds_read_b32 v8, v128 offset:34840
	ds_read_b32 v7, v128 offset:34844
	ds_read_b32 v10, v128 offset:34848
	ds_read_b32 v9, v128 offset:34852
	ds_read_b32 v12, v128 offset:34856
	ds_read_b32 v11, v128 offset:34860
	ds_read_b32 v14, v128 offset:34864
	ds_read_b32 v13, v128 offset:34868
	ds_read_b32 v129, v128 offset:34872
	ds_read_b32 v15, v128 offset:34876
	s_waitcnt lgkmcnt(0)
	v_cmp_ge_i32_e64 s[38:39], v147, v142
	v_cmp_ge_i32_e32 vcc, v142, v147
	s_nop 1
	s_and_b64 s[38:39], s[38:39], s[10:11]
	s_andn2_b64 vcc, vcc, s[10:11]
	s_or_b64 vcc, vcc, s[38:39]
	v_mul_f32_e32 v2, v236, v2
	v_mul_f32_e32 v2, v80, v2
	v_cndmask_b32_e32 v2, 0, v2, vcc
	v_cmp_gt_i32_e64 s[38:39], v147, v142
	v_cmp_ge_i32_e32 vcc, v191, v147
	s_nop 1
	s_and_b64 s[38:39], s[38:39], s[10:11]
	s_andn2_b64 vcc, vcc, s[10:11]
	s_or_b64 vcc, vcc, s[38:39]
	v_mul_f32_e32 v0, v236, v0
	v_mul_f32_e32 v0, v81, v0
	v_cndmask_b32_e32 v0, 0, v0, vcc
	v_cmp_ge_i32_e64 s[38:39], v147, v192
	v_cmp_ge_i32_e32 vcc, v192, v147
	s_nop 1
	s_and_b64 s[38:39], s[38:39], s[10:11]
	s_andn2_b64 vcc, vcc, s[10:11]
	s_or_b64 vcc, vcc, s[38:39]
	v_mul_f32_e32 v4, v236, v4
	v_mul_f32_e32 v4, v82, v4
	v_cndmask_b32_e32 v4, 0, v4, vcc
	v_cmp_ge_i32_e64 s[38:39], v147, v193
	v_cmp_ge_i32_e32 vcc, v193, v147
	s_nop 1
	s_and_b64 s[38:39], s[38:39], s[10:11]
	s_andn2_b64 vcc, vcc, s[10:11]
	s_or_b64 vcc, vcc, s[38:39]
	v_mul_f32_e32 v3, v236, v3
	v_mul_f32_e32 v3, v83, v3
	v_cndmask_b32_e32 v3, 0, v3, vcc
	v_cmp_ge_i32_e64 s[38:39], v147, v197
	v_cmp_ge_i32_e32 vcc, v197, v147
	s_nop 1
	s_and_b64 s[38:39], s[38:39], s[10:11]
	s_andn2_b64 vcc, vcc, s[10:11]
	s_or_b64 vcc, vcc, s[38:39]
	v_mul_f32_e32 v6, v236, v6
	v_mul_f32_e32 v6, v84, v6
	v_cndmask_b32_e32 v6, 0, v6, vcc
	v_cmp_ge_i32_e64 s[38:39], v147, v198
	v_cmp_ge_i32_e32 vcc, v198, v147
	s_nop 1
	s_and_b64 s[38:39], s[38:39], s[10:11]
	s_andn2_b64 vcc, vcc, s[10:11]
	s_or_b64 vcc, vcc, s[38:39]
	v_mul_f32_e32 v5, v236, v5
	v_mul_f32_e32 v5, v85, v5
	v_cndmask_b32_e32 v5, 0, v5, vcc
	v_cmp_ge_i32_e64 s[38:39], v147, v199
	v_cmp_ge_i32_e32 vcc, v199, v147
	s_nop 1
	s_and_b64 s[38:39], s[38:39], s[10:11]
	s_andn2_b64 vcc, vcc, s[10:11]
	s_or_b64 vcc, vcc, s[38:39]
	v_mul_f32_e32 v8, v236, v8
	v_mul_f32_e32 v8, v86, v8
	v_cndmask_b32_e32 v8, 0, v8, vcc
	v_cmp_ge_i32_e64 s[38:39], v147, v200
	v_cmp_ge_i32_e32 vcc, v200, v147
	s_nop 1
	s_and_b64 s[38:39], s[38:39], s[10:11]
	s_andn2_b64 vcc, vcc, s[10:11]
	s_or_b64 vcc, vcc, s[38:39]
	v_mul_f32_e32 v7, v236, v7
	v_mul_f32_e32 v7, v87, v7
	v_cndmask_b32_e32 v7, 0, v7, vcc
	v_cmp_ge_i32_e64 s[38:39], v147, v201
	v_cmp_ge_i32_e32 vcc, v201, v147
	s_nop 1
	s_and_b64 s[38:39], s[38:39], s[10:11]
	s_andn2_b64 vcc, vcc, s[10:11]
	s_or_b64 vcc, vcc, s[38:39]
	v_mul_f32_e32 v10, v236, v10
	v_mul_f32_e32 v10, v88, v10
	v_cndmask_b32_e32 v10, 0, v10, vcc
	v_cmp_ge_i32_e64 s[38:39], v147, v202
	v_cmp_ge_i32_e32 vcc, v202, v147
	s_nop 1
	s_and_b64 s[38:39], s[38:39], s[10:11]
	s_andn2_b64 vcc, vcc, s[10:11]
	s_or_b64 vcc, vcc, s[38:39]
	v_mul_f32_e32 v9, v236, v9
	v_mul_f32_e32 v9, v89, v9
	v_cndmask_b32_e32 v9, 0, v9, vcc
	v_cmp_ge_i32_e64 s[38:39], v147, v203
	v_cmp_ge_i32_e32 vcc, v203, v147
	s_nop 1
	s_and_b64 s[38:39], s[38:39], s[10:11]
	s_andn2_b64 vcc, vcc, s[10:11]
	s_or_b64 vcc, vcc, s[38:39]
	v_mul_f32_e32 v12, v236, v12
	v_mul_f32_e32 v12, v90, v12
	v_cndmask_b32_e32 v12, 0, v12, vcc
	v_cmp_ge_i32_e64 s[38:39], v147, v204
	v_cmp_ge_i32_e32 vcc, v204, v147
	s_nop 1
	s_and_b64 s[38:39], s[38:39], s[10:11]
	s_andn2_b64 vcc, vcc, s[10:11]
	s_or_b64 vcc, vcc, s[38:39]
	v_mul_f32_e32 v11, v236, v11
	v_mul_f32_e32 v11, v91, v11
	v_cndmask_b32_e32 v11, 0, v11, vcc
	v_cmp_ge_i32_e64 s[38:39], v147, v205
	v_cmp_ge_i32_e32 vcc, v205, v147
	s_nop 1
	s_and_b64 s[38:39], s[38:39], s[10:11]
	s_andn2_b64 vcc, vcc, s[10:11]
	s_or_b64 vcc, vcc, s[38:39]
	v_mul_f32_e32 v14, v236, v14
	v_mul_f32_e32 v14, v92, v14
	v_cndmask_b32_e32 v14, 0, v14, vcc
	v_cmp_ge_i32_e64 s[38:39], v147, v206
	v_cmp_ge_i32_e32 vcc, v206, v147
	s_nop 1
	s_and_b64 s[38:39], s[38:39], s[10:11]
	s_andn2_b64 vcc, vcc, s[10:11]
	s_or_b64 vcc, vcc, s[38:39]
	v_mul_f32_e32 v13, v236, v13
	v_mul_f32_e32 v13, v93, v13
	v_cndmask_b32_e32 v13, 0, v13, vcc
	v_cmp_ge_i32_e64 s[38:39], v147, v207
	v_cmp_ge_i32_e32 vcc, v207, v147
	s_nop 1
	s_and_b64 s[38:39], s[38:39], s[10:11]
	s_andn2_b64 vcc, vcc, s[10:11]
	s_or_b64 vcc, vcc, s[38:39]
	v_mul_f32_e32 v129, v236, v129
	v_mul_f32_e32 v129, v94, v129
	v_cndmask_b32_e32 v80, 0, v129, vcc
	v_cmp_ge_i32_e64 s[38:39], v147, v208
	v_cmp_ge_i32_e32 vcc, v208, v147
	s_nop 1
	s_and_b64 s[38:39], s[38:39], s[10:11]
	s_andn2_b64 vcc, vcc, s[10:11]
	s_or_b64 vcc, vcc, s[38:39]
	v_mul_f32_e32 v15, v236, v15
	v_mul_f32_e32 v15, v95, v15
	v_cndmask_b32_e32 v15, 0, v15, vcc
	v_cvt_pk_bf16_f32 v82, v2, v0
	v_cvt_pk_bf16_f32 v83, v4, v3
	v_cvt_pk_bf16_f32 v84, v6, v5
	v_cvt_pk_bf16_f32 v85, v8, v7
	s_nop 1
	v_add_u32_e32 v0, v188, v189
	v_add_u32_e32 v0, 0xd000, v0
	ds_read2_b64 v[2:5], v0 offset1:2
	s_waitcnt lgkmcnt(0)
	v_mfma_f32_32x32x16_bf16 v[64:79], v[2:5], v[82:85], v[64:79]
	v_cvt_pk_bf16_f32 v2, v10, v9
	v_cvt_pk_bf16_f32 v3, v12, v11
	v_cvt_pk_bf16_f32 v4, v14, v13
	v_cvt_pk_bf16_f32 v5, v80, v15
	s_nop 1
	ds_read2_b64 v[6:9], v0 offset0:4 offset1:6
	s_waitcnt lgkmcnt(0)
	v_mfma_f32_32x32x16_bf16 v[64:79], v[6:9], v[2:5], v[64:79]
; DI void phase_ret_chunk(PrmC p, int ri, unsigned char* smem, bool skip_ctx_out) {
;     ...
;             if (use1) {
; #pragma unroll
;                 for (int i = 0; i < 16; ++i) { const int j = 32 + (i & 3) + 8 * (i >> 2) + 4 * hh; const bool keep = dir ? (j >= iil) : (iil >= j); Sx1[i] = keep ? Sx1[i] * (gi1 * gtab[hh * 16 + i]) : 0.f; }
.LBB0_414:
	s_or_b64 exec, exec, s[18:19]
	s_and_saveexec_b64 s[18:19], s[14:15]
	s_cbranch_execz .LBB0_335
	v_add_u32_e32 v128, v132, v187
	ds_read_b32 v2, v128 offset:34816
	ds_read_b32 v0, v128 offset:34820
	ds_read_b32 v5, v128 offset:34824
	ds_read_b32 v4, v128 offset:34828
	ds_read_b32 v7, v128 offset:34832
	ds_read_b32 v6, v128 offset:34836
	ds_read_b32 v9, v128 offset:34840
	ds_read_b32 v8, v128 offset:34844
	ds_read_b32 v11, v128 offset:34848
	ds_read_b32 v10, v128 offset:34852
	ds_read_b32 v13, v128 offset:34856
	ds_read_b32 v12, v128 offset:34860
	ds_read_b32 v15, v128 offset:34864
	ds_read_b32 v14, v128 offset:34868
	ds_read_b32 v129, v128 offset:34872
	ds_read_b32 v130, v128 offset:34876
	s_waitcnt lgkmcnt(0)
	v_cmp_ge_i32_e64 s[38:39], v147, v190
	v_cmp_ge_i32_e32 vcc, v190, v147
	s_nop 1
	s_and_b64 s[38:39], s[38:39], s[10:11]
	s_andn2_b64 vcc, vcc, s[10:11]
	s_or_b64 vcc, vcc, s[38:39]
	v_mul_f32_e32 v2, v145, v2
	v_mul_f32_e32 v2, v48, v2
	v_cndmask_b32_e32 v2, 0, v2, vcc
	v_cmp_ge_i32_e64 s[38:39], v147, v209
	v_cmp_ge_i32_e32 vcc, v209, v147
	s_nop 1
	s_and_b64 s[38:39], s[38:39], s[10:11]
	s_andn2_b64 vcc, vcc, s[10:11]
	s_or_b64 vcc, vcc, s[38:39]
	v_mul_f32_e32 v0, v145, v0
	v_mul_f32_e32 v0, v49, v0
	v_cndmask_b32_e32 v0, 0, v0, vcc
	v_cmp_ge_i32_e64 s[38:39], v147, v210
	v_cmp_ge_i32_e32 vcc, v210, v147
	s_nop 1
	s_and_b64 s[38:39], s[38:39], s[10:11]
	s_andn2_b64 vcc, vcc, s[10:11]
	s_or_b64 vcc, vcc, s[38:39]
	v_mul_f32_e32 v5, v145, v5
	v_mul_f32_e32 v5, v50, v5
	v_cndmask_b32_e32 v5, 0, v5, vcc
	v_cmp_ge_i32_e64 s[38:39], v147, v211
	v_cmp_ge_i32_e32 vcc, v211, v147
	s_nop 1
	s_and_b64 s[38:39], s[38:39], s[10:11]
	s_andn2_b64 vcc, vcc, s[10:11]
	s_or_b64 vcc, vcc, s[38:39]
	v_mul_f32_e32 v4, v145, v4
	v_mul_f32_e32 v4, v51, v4
	v_cndmask_b32_e32 v4, 0, v4, vcc
	v_cmp_ge_i32_e64 s[38:39], v147, v212
	v_cmp_ge_i32_e32 vcc, v212, v147
	s_nop 1
	s_and_b64 s[38:39], s[38:39], s[10:11]
	s_andn2_b64 vcc, vcc, s[10:11]
	s_or_b64 vcc, vcc, s[38:39]
	v_mul_f32_e32 v7, v145, v7
	v_mul_f32_e32 v7, v52, v7
	v_cndmask_b32_e32 v7, 0, v7, vcc
	v_cmp_ge_i32_e64 s[38:39], v147, v213
	v_cmp_ge_i32_e32 vcc, v213, v147
	s_nop 1
	s_and_b64 s[38:39], s[38:39], s[10:11]
	s_andn2_b64 vcc, vcc, s[10:11]
	s_or_b64 vcc, vcc, s[38:39]
	v_mul_f32_e32 v6, v145, v6
	v_mul_f32_e32 v6, v53, v6
	v_cndmask_b32_e32 v6, 0, v6, vcc
	v_cmp_ge_i32_e64 s[38:39], v147, v214
	v_cmp_ge_i32_e32 vcc, v214, v147
	s_nop 1
	s_and_b64 s[38:39], s[38:39], s[10:11]
	s_andn2_b64 vcc, vcc, s[10:11]
	s_or_b64 vcc, vcc, s[38:39]
	v_mul_f32_e32 v9, v145, v9
	v_mul_f32_e32 v9, v54, v9
	v_cndmask_b32_e32 v9, 0, v9, vcc
	v_cmp_ge_i32_e64 s[38:39], v147, v215
	v_cmp_ge_i32_e32 vcc, v215, v147
	s_nop 1
	s_and_b64 s[38:39], s[38:39], s[10:11]
	s_andn2_b64 vcc, vcc, s[10:11]
	s_or_b64 vcc, vcc, s[38:39]
	v_mul_f32_e32 v8, v145, v8
	v_mul_f32_e32 v8, v55, v8
	v_cndmask_b32_e32 v8, 0, v8, vcc
	v_cmp_ge_i32_e64 s[38:39], v147, v216
	v_cmp_ge_i32_e32 vcc, v216, v147
	s_nop 1
	s_and_b64 s[38:39], s[38:39], s[10:11]
	s_andn2_b64 vcc, vcc, s[10:11]
	s_or_b64 vcc, vcc, s[38:39]
	v_mul_f32_e32 v11, v145, v11
	v_mul_f32_e32 v11, v56, v11
	v_cndmask_b32_e32 v11, 0, v11, vcc
	v_cmp_ge_i32_e64 s[38:39], v147, v217
	v_cmp_ge_i32_e32 vcc, v217, v147
	s_nop 1
	s_and_b64 s[38:39], s[38:39], s[10:11]
	s_andn2_b64 vcc, vcc, s[10:11]
	s_or_b64 vcc, vcc, s[38:39]
	v_mul_f32_e32 v10, v145, v10
	v_mul_f32_e32 v10, v57, v10
	v_cndmask_b32_e32 v10, 0, v10, vcc
	v_cmp_ge_i32_e64 s[38:39], v147, v218
	v_cmp_ge_i32_e32 vcc, v218, v147
	s_nop 1
	s_and_b64 s[38:39], s[38:39], s[10:11]
	s_andn2_b64 vcc, vcc, s[10:11]
	s_or_b64 vcc, vcc, s[38:39]
	v_mul_f32_e32 v13, v145, v13
	v_mul_f32_e32 v13, v58, v13
	v_cndmask_b32_e32 v13, 0, v13, vcc
	v_cmp_ge_i32_e64 s[38:39], v147, v219
	v_cmp_ge_i32_e32 vcc, v219, v147
	s_nop 1
	s_and_b64 s[38:39], s[38:39], s[10:11]
	s_andn2_b64 vcc, vcc, s[10:11]
	s_or_b64 vcc, vcc, s[38:39]
	v_mul_f32_e32 v12, v145, v12
	v_mul_f32_e32 v12, v59, v12
	v_cndmask_b32_e32 v12, 0, v12, vcc
	v_cmp_ge_i32_e64 s[38:39], v147, v220
	v_cmp_ge_i32_e32 vcc, v220, v147
	s_nop 1
	s_and_b64 s[38:39], s[38:39], s[10:11]
	s_andn2_b64 vcc, vcc, s[10:11]
	s_or_b64 vcc, vcc, s[38:39]
	v_mul_f32_e32 v15, v145, v15
	v_mul_f32_e32 v15, v60, v15
	v_cndmask_b32_e32 v15, 0, v15, vcc
	v_cmp_ge_i32_e64 s[38:39], v147, v221
	v_cmp_ge_i32_e32 vcc, v221, v147
	s_nop 1
	s_and_b64 s[38:39], s[38:39], s[10:11]
	s_andn2_b64 vcc, vcc, s[10:11]
	s_or_b64 vcc, vcc, s[38:39]
	v_mul_f32_e32 v14, v145, v14
	v_mul_f32_e32 v14, v61, v14
	v_cndmask_b32_e32 v14, 0, v14, vcc
	v_cmp_ge_i32_e64 s[38:39], v147, v222
	v_cmp_ge_i32_e32 vcc, v222, v147
	s_nop 1
	s_and_b64 s[38:39], s[38:39], s[10:11]
	s_andn2_b64 vcc, vcc, s[10:11]
	s_or_b64 vcc, vcc, s[38:39]
	v_mul_f32_e32 v129, v145, v129
	v_mul_f32_e32 v129, v62, v129
	v_cndmask_b32_e32 v49, 0, v129, vcc
	v_cmp_ge_i32_e64 s[38:39], v147, v223
	v_cmp_ge_i32_e32 vcc, v223, v147
	s_nop 1
	s_and_b64 s[38:39], s[38:39], s[10:11]
	s_andn2_b64 vcc, vcc, s[10:11]
	s_or_b64 vcc, vcc, s[38:39]
	v_mul_f32_e32 v130, v145, v130
	v_mul_f32_e32 v130, v63, v130
	v_cndmask_b32_e32 v48, 0, v130, vcc
	s_branch .LBB0_334
